# m1 step-1 loads prefetched one unit ahead into spare VGPRs; scan hand-off split (W/Qd at step end, KdT/QK/u at a mid-step barrier); DPP row-rotate sums in m1 conv
# speedup vs baseline: 1.0087x; 1.0087x over previous
.LBB0_528:
	s_or_b64 exec, exec, s[6:7]
	v_readlane_b32 s6, v255, 9
	v_readlane_b32 s7, v255, 10
	s_andn2_b64 vcc, exec, s[6:7]
	s_waitcnt lgkmcnt(0)
	s_barrier
	s_cbranch_vccnz .LBB0_648
	s_add_u32 s20, s4, 0xec00000
	s_addc_u32 s21, s5, 0
	s_add_u32 s30, s4, 0x2ac00000
	s_addc_u32 s31, s5, 0
	s_add_u32 s34, s4, 0xe900000
	s_addc_u32 s35, s5, 0
	s_add_u32 s22, s4, 0xea00000
	s_addc_u32 s23, s5, 0
	s_mov_b32 s36, s2
	s_mov_b32 s24, s2
	v_mbcnt_lo_u32_b32 v247, -1, 0
	v_mbcnt_hi_u32_b32 v247, -1, v247
	v_lshlrev_b32_e32 v243, 5, v247
	v_or_b32_e32 v247, s33, v247
	v_add_u32_e32 v248, 0, v247
	v_mul_hi_u32 v249, v248, s65
	v_lshrrev_b32_e32 v249, 3, v249
	v_mul_u32_u24_e32 v250, 48, v249
	v_sub_u32_e32 v250, v248, v250
	v_lshrrev_b32_e32 v251, 4, v250
	v_and_b32_e32 v250, 15, v250
	v_lshlrev_b32_e32 v251, 10, v251
	v_lshl_or_b32 v250, v250, 4, v251
	v_mad_u32_u24 v230, v249, s58, v250
	v_add_u32_e32 v248, 512, v247
	v_mul_hi_u32 v249, v248, s65
	v_lshrrev_b32_e32 v249, 3, v249
	v_mul_u32_u24_e32 v250, 48, v249
	v_sub_u32_e32 v250, v248, v250
	v_lshrrev_b32_e32 v251, 4, v250
	v_and_b32_e32 v250, 15, v250
	v_lshlrev_b32_e32 v251, 10, v251
	v_lshl_or_b32 v250, v250, 4, v251
	v_mad_u32_u24 v231, v249, s58, v250
	v_add_u32_e32 v248, 1024, v247
	v_mul_hi_u32 v249, v248, s65
	v_lshrrev_b32_e32 v249, 3, v249
	v_mul_u32_u24_e32 v250, 48, v249
	v_sub_u32_e32 v250, v248, v250
	v_lshrrev_b32_e32 v251, 4, v250
	v_and_b32_e32 v250, 15, v250
	v_lshlrev_b32_e32 v251, 10, v251
	v_lshl_or_b32 v250, v250, 4, v251
	v_mad_u32_u24 v232, v249, s58, v250
	v_add_u32_e32 v248, 1536, v247
	v_mul_hi_u32 v249, v248, s65
	v_lshrrev_b32_e32 v249, 3, v249
	v_mul_u32_u24_e32 v250, 48, v249
	v_sub_u32_e32 v250, v248, v250
	v_lshrrev_b32_e32 v251, 4, v250
	v_and_b32_e32 v250, 15, v250
	v_lshlrev_b32_e32 v251, 10, v251
	v_lshl_or_b32 v250, v250, 4, v251
	v_mad_u32_u24 v233, v249, s58, v250
	v_add_u32_e32 v248, 2048, v247
	v_mul_hi_u32 v249, v248, s65
	v_lshrrev_b32_e32 v249, 3, v249
	v_mul_u32_u24_e32 v250, 48, v249
	v_sub_u32_e32 v250, v248, v250
	v_lshrrev_b32_e32 v251, 4, v250
	v_and_b32_e32 v250, 15, v250
	v_lshlrev_b32_e32 v251, 10, v251
	v_lshl_or_b32 v250, v250, 4, v251
	v_mad_u32_u24 v234, v249, s58, v250
	v_add_u32_e32 v248, 2560, v247
	v_mul_hi_u32 v249, v248, s65
	v_lshrrev_b32_e32 v249, 3, v249
	v_mul_u32_u24_e32 v250, 48, v249
	v_sub_u32_e32 v250, v248, v250
	v_lshrrev_b32_e32 v251, 4, v250
	v_and_b32_e32 v250, 15, v250
	v_lshlrev_b32_e32 v251, 10, v251
	v_lshl_or_b32 v250, v250, 4, v251
	v_mad_u32_u24 v235, v249, s58, v250
	v_add_u32_e32 v248, 3072, v247
	v_mul_hi_u32 v249, v248, s65
	v_lshrrev_b32_e32 v249, 3, v249
	v_mul_u32_u24_e32 v250, 48, v249
	v_sub_u32_e32 v250, v248, v250
	v_lshrrev_b32_e32 v251, 4, v250
	v_and_b32_e32 v250, 15, v250
	v_lshlrev_b32_e32 v251, 10, v251
	v_lshl_or_b32 v250, v250, 4, v251
	v_mad_u32_u24 v242, v249, s58, v250
	s_mov_b32 s46, s24
	s_ashr_i32 s47, s46, 9
	s_lshl_b32 s47, s47, 13
	s_lshl_b32 s48, s46, 4
	s_and_b32 s48, s48, 0x1fc0
	s_add_i32 s47, s47, s48
	s_and_b32 s48, s46, 3
	s_cmp_lg_u32 s33, 0
	s_cbranch_scc1 .Lm1pf_nobg_pro
	s_lshl_b32 s55, s47, 5
	s_lshl_b32 s54, s48, 2
	s_add_u32 s55, s55, s54
	s_add_u32 s60, s22, s55
	s_addc_u32 s61, s23, 0
	global_load_dword v190, v243, s[60:61]
	global_load_dword v191, v243, s[60:61] offset:16
.Lm1pf_nobg_pro:
	s_add_i32 s47, s47, -3
	s_mul_hi_i32 s86, s47, 0xc00
	s_mul_i32 s55, s47, 0xc00
	s_lshl_b32 s54, s48, 8
	s_add_u32 s55, s55, s54
	s_addc_u32 s86, s86, 0
	s_add_u32 s60, s20, s55
	s_addc_u32 s61, s21, s86
	global_load_dwordx4 v[202:205], v230, s[60:61]
	global_load_dwordx4 v[206:209], v231, s[60:61]
	global_load_dwordx4 v[210:213], v232, s[60:61]
	global_load_dwordx4 v[214:217], v233, s[60:61]
	global_load_dwordx4 v[218:221], v234, s[60:61]
	global_load_dwordx4 v[222:225], v235, s[60:61]
	global_load_dwordx4 v[226:229], v242, s[60:61]
	s_waitcnt vmcnt(0)
	s_branch .LBB0_531

.LBB0_531:
	s_mov_b32 s4, -1
	s_waitcnt vmcnt(2)
	s_ashr_i32 s6, s24, 9
	v_mbcnt_lo_u32_b32 v0, s4, 0
	v_mbcnt_hi_u32_b32 v0, s4, v0
	v_or_b32_e32 v64, s33, v0
	s_ashr_i32 s7, s6, 31
	s_lshl_b32 s5, s24, 4
	s_and_b32 s4, s24, 3
	v_readfirstlane_b32 s25, v64
	s_lshl_b64 s[28:29], s[6:7], 13
	s_and_b32 s18, s5, 0x1fc0
	s_cmp_lt_u32 s25, 64
	v_and_b32_e32 v36, 63, v64
	v_mov_b32_e32 v0, 0
	s_cselect_b64 s[26:27], -1, 0
	s_cmp_gt_u32 s25, 63
	v_mov_b32_e32 v29, 0
	v_mov_b32_e32 v28, 0
	s_cbranch_scc1 .LBB0_533
	v_or_b32_e32 v1, s18, v36
	v_or_b32_e32 v2, s28, v1
	v_mov_b32_e32 v3, s29
	v_lshlrev_b64 v[2:3], 5, v[2:3]
	v_lshl_add_u64 v[2:3], s[22:23], 0, v[2:3]
	s_lshl_b32 s68, s4, 2
	v_lshl_add_u64 v[2:3], v[2:3], 0, s[68:69]
	v_mov_b32_e32 v28, v190
	v_mov_b32_e32 v29, v191
.LBB0_533:
	v_mul_hi_i32 v4, v64, s65
	v_lshrrev_b32_e32 v5, 31, v4
	v_ashrrev_i32_e32 v1, 3, v4
	s_add_i32 s18, s18, -3
	v_add_u32_e32 v30, v1, v5
	s_lshl_b32 s37, s4, 7
	v_add_u32_e32 v192, s18, v30
	s_movk_i32 s4, 0xc90
	v_cmp_gt_i32_e32 vcc, s4, v64
	v_cmp_lt_i32_e64 s[4:5], -1, v192
	s_and_b64 s[6:7], vcc, s[4:5]
	v_mov_b32_e32 v1, 0
	v_mov_b32_e32 v2, 0
	v_mov_b32_e32 v3, 0
	s_and_saveexec_b64 s[4:5], s[6:7]
	s_cbranch_execz .LBB0_535
	v_lshrrev_b32_e32 v0, 3, v4
	v_add_u32_e32 v0, v0, v5
	v_mul_lo_u32 v0, v0, 48
	v_sub_u32_e32 v4, v64, v0
	v_lshl_add_u64 v[0:1], s[28:29], 0, v[192:193]
	v_mov_b64_e32 v[2:3], s[20:21]
	v_mad_u64_u32 v[2:3], s[6:7], v0, s58, v[2:3]
	v_lshlrev_b32_e32 v0, 5, v4
	v_and_b32_e32 v0, 0xfffffe00, v0
	v_mad_i32_i24 v3, v1, s58, v3
	v_ashrrev_i32_e32 v1, 31, v0
	v_lshl_add_u64 v[0:1], v[0:1], 1, v[2:3]
	s_lshl_b32 s68, s37, 1
	v_lshlrev_b32_e32 v2, 4, v4
	v_lshl_add_u64 v[0:1], v[0:1], 0, s[68:69]
	v_and_b32_e32 v192, 0xf0, v2
	v_lshl_add_u64 v[0:1], v[0:1], 0, v[192:193]
	v_mov_b64_e32 v[0:1], v[202:203]
	v_mov_b64_e32 v[2:3], v[204:205]
.LBB0_535:
	s_or_b64 exec, exec, s[4:5]
	v_add_u32_e32 v31, 0x200, v64
	v_mul_hi_i32 v5, v31, s65
	v_lshrrev_b32_e32 v6, 31, v5
	v_ashrrev_i32_e32 v4, 3, v5
	v_add_u32_e32 v32, v4, v6
	v_add_u32_e32 v192, s18, v32
	s_movk_i32 s4, 0xa90
	v_cmp_gt_i32_e64 s[4:5], s4, v64
	v_cmp_lt_i32_e64 s[6:7], -1, v192
	s_and_b64 s[8:9], s[4:5], s[6:7]
	v_mov_b32_e32 v4, 0
	v_mov_b32_e32 v8, 0
	v_mov_b32_e32 v9, 0
	v_mov_b32_e32 v10, 0
	v_mov_b32_e32 v11, 0
	s_and_saveexec_b64 s[6:7], s[8:9]
	s_cbranch_execz .LBB0_537
	v_lshrrev_b32_e32 v5, 3, v5
	v_add_u32_e32 v5, v5, v6
	v_mul_lo_u32 v5, v5, 48
	v_sub_u32_e32 v5, v31, v5
	v_lshl_add_u64 v[6:7], s[28:29], 0, v[192:193]
	v_mov_b64_e32 v[8:9], s[20:21]
	v_mad_u64_u32 v[8:9], s[8:9], v6, s58, v[8:9]
	v_lshlrev_b32_e32 v6, 5, v5
	v_and_b32_e32 v6, 0xfffffe00, v6
	v_mad_i32_i24 v9, v7, s58, v9
	v_ashrrev_i32_e32 v7, 31, v6
	v_lshl_add_u64 v[6:7], v[6:7], 1, v[8:9]
	s_lshl_b32 s68, s37, 1
	v_lshlrev_b32_e32 v5, 4, v5
	v_lshl_add_u64 v[6:7], v[6:7], 0, s[68:69]
	v_and_b32_e32 v192, 0xf0, v5
	v_lshl_add_u64 v[6:7], v[6:7], 0, v[192:193]
	v_mov_b64_e32 v[8:9], v[206:207]
	v_mov_b64_e32 v[10:11], v[208:209]
.LBB0_537:
	s_or_b64 exec, exec, s[6:7]
	v_add_u32_e32 v33, 0x400, v64
	v_mul_hi_i32 v12, v33, s65
	v_lshrrev_b32_e32 v13, 31, v12
	v_ashrrev_i32_e32 v5, 3, v12
	v_add_u32_e32 v34, v5, v13
	v_add_u32_e32 v192, s18, v34
	s_movk_i32 s6, 0x890
	v_cmp_gt_i32_e64 s[6:7], s6, v64
	v_cmp_lt_i32_e64 s[8:9], -1, v192
	s_and_b64 s[10:11], s[6:7], s[8:9]
	v_mov_b32_e32 v5, 0
	v_mov_b32_e32 v6, 0
	v_mov_b32_e32 v7, 0
	s_and_saveexec_b64 s[8:9], s[10:11]
	s_cbranch_execz .LBB0_539
	v_lshrrev_b32_e32 v4, 3, v12
	v_add_u32_e32 v4, v4, v13
	v_mul_lo_u32 v4, v4, 48
	v_sub_u32_e32 v12, v33, v4
	v_lshl_add_u64 v[4:5], s[28:29], 0, v[192:193]
	v_mov_b64_e32 v[6:7], s[20:21]
	v_mad_u64_u32 v[6:7], s[10:11], v4, s58, v[6:7]
	v_lshlrev_b32_e32 v4, 5, v12
	v_and_b32_e32 v4, 0xfffffe00, v4
	v_mad_i32_i24 v7, v5, s58, v7
	v_ashrrev_i32_e32 v5, 31, v4
	v_lshl_add_u64 v[4:5], v[4:5], 1, v[6:7]
	s_lshl_b32 s68, s37, 1
	v_lshlrev_b32_e32 v6, 4, v12
	v_lshl_add_u64 v[4:5], v[4:5], 0, s[68:69]
	v_and_b32_e32 v192, 0xf0, v6
	v_lshl_add_u64 v[4:5], v[4:5], 0, v[192:193]
	v_mov_b64_e32 v[4:5], v[210:211]
	v_mov_b64_e32 v[6:7], v[212:213]
.LBB0_539:
	s_or_b64 exec, exec, s[8:9]
	v_add_u32_e32 v35, 0x600, v64
	v_mul_hi_i32 v13, v35, s65
	v_lshrrev_b32_e32 v14, 31, v13
	v_ashrrev_i32_e32 v12, 3, v13
	v_add_u32_e32 v37, v12, v14
	v_add_u32_e32 v192, s18, v37
	s_movk_i32 s8, 0x690
	v_cmp_gt_i32_e64 s[8:9], s8, v64
	v_cmp_lt_i32_e64 s[10:11], -1, v192
	s_and_b64 s[12:13], s[8:9], s[10:11]
	v_mov_b32_e32 v12, 0
	v_mov_b32_e32 v16, 0
	v_mov_b32_e32 v17, 0
	v_mov_b32_e32 v18, 0
	v_mov_b32_e32 v19, 0
	s_and_saveexec_b64 s[10:11], s[12:13]
	s_cbranch_execz .LBB0_541
	v_lshrrev_b32_e32 v13, 3, v13
	v_add_u32_e32 v13, v13, v14
	v_mul_lo_u32 v13, v13, 48
	v_sub_u32_e32 v13, v35, v13
	v_lshl_add_u64 v[14:15], s[28:29], 0, v[192:193]
	v_mov_b64_e32 v[16:17], s[20:21]
	v_mad_u64_u32 v[16:17], s[12:13], v14, s58, v[16:17]
	v_lshlrev_b32_e32 v14, 5, v13
	v_and_b32_e32 v14, 0xfffffe00, v14
	v_mad_i32_i24 v17, v15, s58, v17
	v_ashrrev_i32_e32 v15, 31, v14
	v_lshl_add_u64 v[14:15], v[14:15], 1, v[16:17]
	s_lshl_b32 s68, s37, 1
	v_lshlrev_b32_e32 v13, 4, v13
	v_lshl_add_u64 v[14:15], v[14:15], 0, s[68:69]
	v_and_b32_e32 v192, 0xf0, v13
	v_lshl_add_u64 v[14:15], v[14:15], 0, v[192:193]
	v_mov_b64_e32 v[16:17], v[214:215]
	v_mov_b64_e32 v[18:19], v[216:217]
.LBB0_541:
	s_or_b64 exec, exec, s[10:11]
	v_add_u32_e32 v38, 0x800, v64
	v_mul_hi_i32 v20, v38, s65
	v_lshrrev_b32_e32 v21, 31, v20
	v_ashrrev_i32_e32 v13, 3, v20
	v_add_u32_e32 v39, v13, v21
	v_add_u32_e32 v192, s18, v39
	s_movk_i32 s10, 0x490
	v_cmp_gt_i32_e64 s[10:11], s10, v64
	v_cmp_lt_i32_e64 s[12:13], -1, v192
	s_and_b64 s[14:15], s[10:11], s[12:13]
	v_mov_b32_e32 v13, 0
	v_mov_b32_e32 v14, 0
	v_mov_b32_e32 v15, 0
	s_and_saveexec_b64 s[12:13], s[14:15]
	s_cbranch_execz .LBB0_543
	v_lshrrev_b32_e32 v12, 3, v20
	v_add_u32_e32 v12, v12, v21
	v_mul_lo_u32 v12, v12, 48
	v_sub_u32_e32 v20, v38, v12
	v_lshl_add_u64 v[12:13], s[28:29], 0, v[192:193]
	v_mov_b64_e32 v[14:15], s[20:21]
	v_mad_u64_u32 v[14:15], s[14:15], v12, s58, v[14:15]
	v_lshlrev_b32_e32 v12, 5, v20
	v_and_b32_e32 v12, 0xfffffe00, v12
	v_mad_i32_i24 v15, v13, s58, v15
	v_ashrrev_i32_e32 v13, 31, v12
	v_lshl_add_u64 v[12:13], v[12:13], 1, v[14:15]
	s_lshl_b32 s68, s37, 1
	v_lshlrev_b32_e32 v14, 4, v20
	v_lshl_add_u64 v[12:13], v[12:13], 0, s[68:69]
	v_and_b32_e32 v192, 0xf0, v14
	v_lshl_add_u64 v[12:13], v[12:13], 0, v[192:193]
	v_mov_b64_e32 v[12:13], v[218:219]
	v_mov_b64_e32 v[14:15], v[220:221]
.LBB0_543:
	s_or_b64 exec, exec, s[12:13]
	v_add_u32_e32 v40, 0xa00, v64
	v_mul_hi_i32 v21, v40, s65
	v_lshrrev_b32_e32 v22, 31, v21
	v_ashrrev_i32_e32 v20, 3, v21
	v_add_u32_e32 v41, v20, v22
	v_add_u32_e32 v192, s18, v41
	s_movk_i32 s12, 0x290
	v_cmp_gt_i32_e64 s[12:13], s12, v64
	v_cmp_lt_i32_e64 s[14:15], -1, v192
	s_and_b64 s[38:39], s[12:13], s[14:15]
	v_mov_b32_e32 v20, 0
	v_mov_b32_e32 v24, 0
	v_mov_b32_e32 v25, 0
	v_mov_b32_e32 v26, 0
	v_mov_b32_e32 v27, 0
	s_and_saveexec_b64 s[14:15], s[38:39]
	s_cbranch_execz .LBB0_545
	v_lshrrev_b32_e32 v21, 3, v21
	v_add_u32_e32 v21, v21, v22
	v_mul_lo_u32 v21, v21, 48
	v_sub_u32_e32 v21, v40, v21
	v_lshl_add_u64 v[22:23], s[28:29], 0, v[192:193]
	v_mov_b64_e32 v[24:25], s[20:21]
	v_mad_u64_u32 v[24:25], s[38:39], v22, s58, v[24:25]
	v_lshlrev_b32_e32 v22, 5, v21
	v_and_b32_e32 v22, 0xfffffe00, v22
	v_mad_i32_i24 v25, v23, s58, v25
	v_ashrrev_i32_e32 v23, 31, v22
	v_lshl_add_u64 v[22:23], v[22:23], 1, v[24:25]
	s_lshl_b32 s68, s37, 1
	v_lshlrev_b32_e32 v21, 4, v21
	v_lshl_add_u64 v[22:23], v[22:23], 0, s[68:69]
	v_and_b32_e32 v192, 0xf0, v21
	v_lshl_add_u64 v[22:23], v[22:23], 0, v[192:193]
	v_mov_b64_e32 v[24:25], v[222:223]
	v_mov_b64_e32 v[26:27], v[224:225]

.LBB0_554:
	v_cmp_ne_u32_e32 vcc, 0, v36
	v_lshl_add_u32 v2, v36, 2, 0
	v_add_u32_e32 v3, 0x19600, v2
	v_subbrev_co_u32_e64 v0, s[4:5], 0, v36, vcc
	v_lshlrev_b32_e32 v0, 2, v0
	ds_bpermute_b32 v0, v0, v29
	s_waitcnt lgkmcnt(0)
	v_add_f32_e32 v0, v29, v0
	v_cndmask_b32_e32 v0, v29, v0, vcc
	v_cmp_gt_u32_e32 vcc, 2, v36
	s_nop 1
	v_cndmask_b32_e64 v1, -2, 0, vcc
	v_add_lshl_u32 v1, v1, v36, 2
	ds_bpermute_b32 v1, v1, v0
	s_waitcnt lgkmcnt(0)
	v_add_f32_e32 v1, v0, v1
	v_cndmask_b32_e32 v0, v1, v0, vcc
	v_cmp_gt_u32_e32 vcc, 4, v36
	s_nop 1
	v_cndmask_b32_e64 v1, -4, 0, vcc
	v_add_lshl_u32 v1, v1, v36, 2
	ds_bpermute_b32 v1, v1, v0
	s_waitcnt lgkmcnt(0)
	v_add_f32_e32 v1, v0, v1
	v_cndmask_b32_e32 v0, v1, v0, vcc
	v_cmp_gt_u32_e32 vcc, 8, v36
	s_nop 1
	v_cndmask_b32_e64 v1, -8, 0, vcc
	v_add_lshl_u32 v1, v1, v36, 2
	ds_bpermute_b32 v1, v1, v0
	s_waitcnt lgkmcnt(0)
	v_add_f32_e32 v1, v0, v1
	v_cndmask_b32_e32 v0, v1, v0, vcc
	v_cmp_gt_u32_e32 vcc, 16, v36
	s_nop 1
	v_cndmask_b32_e64 v1, -16, 0, vcc
	v_add_lshl_u32 v1, v1, v36, 2
	ds_bpermute_b32 v1, v1, v0
	s_waitcnt lgkmcnt(0)
	v_add_f32_e32 v1, v0, v1
	v_cndmask_b32_e32 v0, v1, v0, vcc
	v_lshlrev_b32_e32 v1, 2, v64
	v_and_b32_e32 v1, 0x7c, v1
	ds_bpermute_b32 v1, v1, v0
	v_cmp_gt_u32_e32 vcc, 32, v36
	s_waitcnt lgkmcnt(0)
	v_add_f32_e32 v1, v0, v1
	v_cndmask_b32_e32 v0, v1, v0, vcc
	v_mul_f32_e32 v1, 0x3fb8aa3b, v0
	v_exp_f32_e32 v1, v1
	ds_write_b32 v3, v0
	v_add_u32_e32 v0, 0x19700, v2
	ds_write_b32 v0, v28
	v_add_u32_e32 v0, 0x19800, v2
	ds_write_b32 v0, v1
	v_mul_f32_e32 v0, v28, v1
	v_add_u32_e32 v1, 0x19900, v2
	ds_write_b32 v1, v0
.LBB0_555:
	v_and_b32_e32 v4, 64, v239
	v_xor_b32_e32 v3, 1, v239
	v_add_u32_e32 v4, 64, v4
	v_cmp_lt_i32_e32 vcc, v3, v4
	s_and_b32 s4, s36, 3
	v_and_b32_e32 v0, 15, v64
	v_cndmask_b32_e32 v3, v239, v3, vcc
	v_lshlrev_b32_e32 v38, 2, v3
	v_xor_b32_e32 v3, 2, v239
	v_cmp_lt_i32_e32 vcc, v3, v4
	v_ashrrev_i32_e32 v1, 4, v64
	s_mulk_i32 s4, 0x1800
	v_cndmask_b32_e32 v3, v239, v3, vcc
	v_lshlrev_b32_e32 v39, 2, v3
	v_xor_b32_e32 v3, 4, v239
	v_cmp_lt_i32_e32 vcc, v3, v4
	s_waitcnt lgkmcnt(0)
	s_barrier
	s_add_i32 s46, s24, s42
	s_cmpk_gt_i32 s46, 0xfff
	s_cbranch_scc1 .Lm1pf_end
	s_ashr_i32 s47, s46, 9
	s_lshl_b32 s47, s47, 13
	s_lshl_b32 s48, s46, 4
	s_and_b32 s48, s48, 0x1fc0
	s_add_i32 s47, s47, s48
	s_and_b32 s48, s46, 3
	s_cmp_lg_u32 s33, 0
	s_cbranch_scc1 .Lm1pf_nobg_loop
	s_lshl_b32 s55, s47, 5
	s_lshl_b32 s54, s48, 2
	s_add_u32 s55, s55, s54
	s_add_u32 s60, s22, s55
	s_addc_u32 s61, s23, 0
	global_load_dword v190, v243, s[60:61]
	global_load_dword v191, v243, s[60:61] offset:16
.Lm1pf_nobg_loop:
	s_add_i32 s47, s47, -3
	s_mul_hi_i32 s86, s47, 0xc00
	s_mul_i32 s55, s47, 0xc00
	s_lshl_b32 s54, s48, 8
	s_add_u32 s55, s55, s54
	s_addc_u32 s86, s86, 0
	s_add_u32 s60, s20, s55
	s_addc_u32 s61, s21, s86
	global_load_dwordx4 v[202:205], v230, s[60:61]
	global_load_dwordx4 v[206:209], v231, s[60:61]
	global_load_dwordx4 v[210:213], v232, s[60:61]
	global_load_dwordx4 v[214:217], v233, s[60:61]
	global_load_dwordx4 v[218:221], v234, s[60:61]
	global_load_dwordx4 v[222:225], v235, s[60:61]
	global_load_dwordx4 v[226:229], v242, s[60:61]
.Lm1pf_end:
	v_lshlrev_b32_e32 v2, 4, v0
	v_cndmask_b32_e32 v3, v239, v3, vcc
	v_lshlrev_b32_e32 v40, 2, v3
	v_xor_b32_e32 v3, 8, v239
	v_cmp_lt_i32_e32 vcc, v3, v4
	v_mul_lo_u32 v42, v1, s62
	s_add_i32 s4, s4, 0
	v_cndmask_b32_e32 v3, v239, v3, vcc
	v_lshlrev_b32_e32 v41, 2, v3
	v_mul_lo_u32 v3, v1, s59
	v_or_b32_e32 v1, v3, v2
	v_add_u32_e32 v37, 0, v2
	s_mov_b32 s6, 0
	v_add_u32_e32 v43, 0, v1
	v_lshl_add_u32 v44, v0, 5, s4
.LBB0_556:
	v_add_u32_e32 v28, s6, v44
	v_add_u32_e32 v0, 0x1a000, v28
	v_add_u32_e32 v4, 0x1a010, v28
	ds_read_b128 v[0:3], v0
	ds_read_b128 v[16:19], v4
	v_add_u32_e32 v4, 0x1a600, v28
	v_add_u32_e32 v8, 0x1a610, v28
	ds_read_b128 v[4:7], v4
	ds_read_b128 v[20:23], v8
	v_add_u32_e32 v8, 0x1ac00, v28
	v_add_u32_e32 v12, 0x1ac10, v28
	ds_read_b128 v[8:11], v8
	ds_read_b128 v[24:27], v12
	v_add_u32_e32 v12, 0x1b200, v28
	v_add_u32_e32 v28, 0x1b210, v28
	ds_read_b128 v[12:15], v12
	ds_read_b128 v[28:31], v28
	ds_read_b128 v[32:35], v43
	ds_read_b128 v[46:49], v43 offset:768
	ds_read_b128 v[50:53], v43 offset:1536
	ds_read_b128 v[54:57], v43 offset:2304
	s_cmpk_eq_i32 s6, 0x200
	s_waitcnt lgkmcnt(3)
	v_lshlrev_b32_e32 v58, 16, v35
	v_and_b32_e32 v59, 0xffff0000, v35
	v_pk_fma_f32 v[58:59], v[18:19], v[58:59], 0 op_sel_hi:[1,1,0]
	s_waitcnt lgkmcnt(2)
	v_lshlrev_b32_e32 v60, 16, v49
	v_and_b32_e32 v61, 0xffff0000, v49
	v_pk_fma_f32 v[58:59], v[22:23], v[60:61], v[58:59]
	s_waitcnt lgkmcnt(1)
	v_lshlrev_b32_e32 v60, 16, v53
	v_and_b32_e32 v61, 0xffff0000, v53
	v_pk_fma_f32 v[58:59], v[26:27], v[60:61], v[58:59]
	s_waitcnt lgkmcnt(0)
	v_lshlrev_b32_e32 v60, 16, v57
	v_and_b32_e32 v61, 0xffff0000, v57
	v_pk_fma_f32 v[58:59], v[30:31], v[60:61], v[58:59]
	v_lshlrev_b32_e32 v62, 16, v34
	v_mul_f32_e32 v35, 0xbfb8aa3b, v58
	v_exp_f32_e32 v35, v35
	v_and_b32_e32 v63, 0xffff0000, v34
	v_and_b32_e32 v49, 0xffff0000, v52
	v_and_b32_e32 v53, 0xffff0000, v33
	v_add_f32_e32 v35, 1.0, v35
	v_rcp_f32_e32 v60, v35
	v_mul_f32_e32 v35, 0xbfb8aa3b, v59
	v_exp_f32_e32 v35, v35
	v_and_b32_e32 v57, 0xffff0000, v47
	s_mov_b32 s4, 0x10e00
	s_cselect_b32 s4, s4, 0x15200
	v_add_f32_e32 v35, 1.0, v35
	v_rcp_f32_e32 v61, v35
	v_pk_fma_f32 v[34:35], v[16:17], v[62:63], 0 op_sel_hi:[1,1,0]
	v_lshlrev_b32_e32 v62, 16, v48
	v_and_b32_e32 v63, 0xffff0000, v48
	v_pk_fma_f32 v[34:35], v[20:21], v[62:63], v[34:35]
	v_lshlrev_b32_e32 v48, 16, v52
	v_lshlrev_b32_e32 v52, 16, v33
	v_pk_fma_f32 v[34:35], v[24:25], v[48:49], v[34:35]
	v_lshlrev_b32_e32 v48, 16, v56
	v_and_b32_e32 v49, 0xffff0000, v56
	v_pk_fma_f32 v[52:53], v[2:3], v[52:53], 0 op_sel_hi:[1,1,0]
	v_lshlrev_b32_e32 v56, 16, v47
	v_pk_fma_f32 v[52:53], v[6:7], v[56:57], v[52:53]
	v_lshlrev_b32_e32 v56, 16, v51
	v_and_b32_e32 v57, 0xffff0000, v51
	v_pk_fma_f32 v[52:53], v[10:11], v[56:57], v[52:53]
	v_lshlrev_b32_e32 v56, 16, v55
	v_and_b32_e32 v57, 0xffff0000, v55
	v_pk_fma_f32 v[52:53], v[14:15], v[56:57], v[52:53]
	v_pk_fma_f32 v[34:35], v[28:29], v[48:49], v[34:35]
	v_mul_f32_e32 v33, 0xbfb8aa3b, v52
	v_exp_f32_e32 v33, v33
	v_mul_f32_e32 v45, 0xbfb8aa3b, v34
	v_exp_f32_e32 v45, v45
	v_lshlrev_b32_e32 v62, 16, v32
	v_add_f32_e32 v33, 1.0, v33
	v_rcp_f32_e32 v56, v33
	v_mul_f32_e32 v33, 0xbfb8aa3b, v53
	v_exp_f32_e32 v33, v33
	v_add_f32_e32 v45, 1.0, v45
	v_rcp_f32_e32 v48, v45
	v_mul_f32_e32 v45, 0xbfb8aa3b, v35
	v_exp_f32_e32 v45, v45
	v_add_f32_e32 v33, 1.0, v33
	v_and_b32_e32 v63, 0xffff0000, v32
	v_rcp_f32_e32 v57, v33
	v_pk_fma_f32 v[32:33], v[0:1], v[62:63], 0 op_sel_hi:[1,1,0]
	v_lshlrev_b32_e32 v62, 16, v46
	v_and_b32_e32 v63, 0xffff0000, v46
	v_pk_fma_f32 v[32:33], v[4:5], v[62:63], v[32:33]
	v_lshlrev_b32_e32 v46, 16, v50
	v_and_b32_e32 v47, 0xffff0000, v50
	v_pk_fma_f32 v[32:33], v[8:9], v[46:47], v[32:33]
	v_lshlrev_b32_e32 v46, 16, v54
	v_and_b32_e32 v47, 0xffff0000, v54
	v_add_f32_e32 v45, 1.0, v45
	v_pk_fma_f32 v[32:33], v[12:13], v[46:47], v[32:33]
	v_rcp_f32_e32 v49, v45
	v_mul_f32_e32 v45, 0xbfb8aa3b, v32
	v_exp_f32_e32 v45, v45
	v_pk_mul_f32 v[52:53], v[52:53], v[56:57]
	v_pk_mul_f32 v[34:35], v[34:35], v[48:49]
	v_pk_mul_f32 v[56:57], v[52:53], v[52:53]
	v_add_f32_e32 v45, 1.0, v45
	v_rcp_f32_e32 v46, v45
	v_mul_f32_e32 v45, 0xbfb8aa3b, v33
	v_exp_f32_e32 v45, v45
	v_pk_mul_f32 v[48:49], v[34:35], v[34:35]
	v_pk_mul_f32 v[58:59], v[58:59], v[60:61]
	s_cmp_lg_u32 s6, 0
	v_add_f32_e32 v45, 1.0, v45
	v_rcp_f32_e32 v47, v45
	v_pk_mul_f32 v[60:61], v[58:59], v[58:59]
	s_cselect_b32 s7, s4, 0xca00
	s_cmpk_eq_i32 s6, 0x400
	v_pk_mul_f32 v[32:33], v[32:33], v[46:47]
	s_cselect_b64 s[4:5], -1, 0
	v_pk_mul_f32 v[46:47], v[32:33], v[32:33]
	s_addk_i32 s6, 0x200
	v_add_f32_e32 v45, v46, v47
	v_add_f32_e32 v45, v56, v45
	v_add_f32_e32 v45, v57, v45
	v_add_f32_e32 v45, v48, v45
	v_add_f32_e32 v45, v49, v45
	v_add_f32_e32 v45, v60, v45
	v_add_f32_e32 v45, v61, v45
	s_cmpk_eq_i32 s6, 0x600
	s_nop 1
	v_add_f32_dpp v45, v45, v45 row_ror:8 row_mask:0xf bank_mask:0xf
	s_nop 1
	v_add_f32_dpp v45, v45, v45 row_ror:4 row_mask:0xf bank_mask:0xf
	s_nop 1
	v_add_f32_dpp v45, v45, v45 row_ror:2 row_mask:0xf bank_mask:0xf
	s_nop 1
	v_add_f32_dpp v45, v45, v45 row_ror:1 row_mask:0xf bank_mask:0xf
	v_add_f32_e32 v45, 0x358637bd, v45
	v_cmp_gt_f32_e32 vcc, s66, v45
	v_mul_f32_e32 v46, 0x4b800000, v45
	s_nop 0
	v_cndmask_b32_e32 v45, v45, v46, vcc
	v_rsq_f32_e32 v45, v45
	s_nop 0
	v_mul_f32_e32 v46, 0x45800000, v45
	v_cndmask_b32_e32 v45, v45, v46, vcc
	v_cndmask_b32_e64 v46, v45, 1.0, s[4:5]
	v_pk_mul_f32 v[32:33], v[32:33], v[46:47] op_sel_hi:[1,0]
	v_pk_mul_f32 v[48:49], v[52:53], v[46:47] op_sel_hi:[1,0]
	v_pk_mul_f32 v[34:35], v[34:35], v[46:47] op_sel_hi:[1,0]
	v_pk_mul_f32 v[46:47], v[58:59], v[46:47] op_sel_hi:[1,0]
	v_cvt_pk_bf16_f32 v32, v32, v33
	v_cvt_pk_bf16_f32 v33, v48, v49
	v_cvt_pk_bf16_f32 v34, v34, v35
	v_cvt_pk_bf16_f32 v35, v46, v47
	v_add3_u32 v45, v37, s7, v42
	ds_write_b128 v45, v[32:35]
	ds_read_b128 v[32:35], v43 offset:24576
	ds_read_b128 v[46:49], v43 offset:25344
	ds_read_b128 v[50:53], v43 offset:26112
	ds_read_b128 v[54:57], v43 offset:26880
	v_add_u32_e32 v43, 0x100, v43
	s_waitcnt lgkmcnt(3)
	v_lshlrev_b32_e32 v58, 16, v35
	v_and_b32_e32 v59, 0xffff0000, v35
	v_pk_fma_f32 v[18:19], v[18:19], v[58:59], 0 op_sel_hi:[1,1,0]
	s_waitcnt lgkmcnt(2)
	v_lshlrev_b32_e32 v58, 16, v49
	v_and_b32_e32 v59, 0xffff0000, v49
	v_pk_fma_f32 v[18:19], v[22:23], v[58:59], v[18:19]
	s_waitcnt lgkmcnt(1)
	v_lshlrev_b32_e32 v22, 16, v53
	v_and_b32_e32 v23, 0xffff0000, v53
	v_pk_fma_f32 v[18:19], v[26:27], v[22:23], v[18:19]
	v_lshlrev_b32_e32 v26, 16, v34
	v_and_b32_e32 v27, 0xffff0000, v34
	v_pk_fma_f32 v[16:17], v[16:17], v[26:27], 0 op_sel_hi:[1,1,0]
	v_lshlrev_b32_e32 v26, 16, v48
	v_and_b32_e32 v27, 0xffff0000, v48
	v_pk_fma_f32 v[16:17], v[20:21], v[26:27], v[16:17]
	v_lshlrev_b32_e32 v20, 16, v52
	v_and_b32_e32 v21, 0xffff0000, v52
	v_pk_fma_f32 v[16:17], v[24:25], v[20:21], v[16:17]
	v_lshlrev_b32_e32 v24, 16, v33
	v_and_b32_e32 v25, 0xffff0000, v33
	v_pk_fma_f32 v[2:3], v[2:3], v[24:25], 0 op_sel_hi:[1,1,0]
	v_lshlrev_b32_e32 v24, 16, v47
	v_and_b32_e32 v25, 0xffff0000, v47
	v_pk_fma_f32 v[2:3], v[6:7], v[24:25], v[2:3]
	v_lshlrev_b32_e32 v6, 16, v51
	v_and_b32_e32 v7, 0xffff0000, v51
	v_pk_fma_f32 v[2:3], v[10:11], v[6:7], v[2:3]
	v_lshlrev_b32_e32 v10, 16, v32
	v_and_b32_e32 v11, 0xffff0000, v32
	v_pk_fma_f32 v[0:1], v[0:1], v[10:11], 0 op_sel_hi:[1,1,0]
	v_lshlrev_b32_e32 v10, 16, v46
	v_and_b32_e32 v11, 0xffff0000, v46
	v_pk_fma_f32 v[0:1], v[4:5], v[10:11], v[0:1]
	v_lshlrev_b32_e32 v4, 16, v50
	v_and_b32_e32 v5, 0xffff0000, v50
	v_pk_fma_f32 v[0:1], v[8:9], v[4:5], v[0:1]
	s_waitcnt lgkmcnt(0)
	v_lshlrev_b32_e32 v4, 16, v54
	v_and_b32_e32 v5, 0xffff0000, v54
	v_lshlrev_b32_e32 v6, 16, v55
	v_and_b32_e32 v7, 0xffff0000, v55
	v_pk_fma_f32 v[0:1], v[12:13], v[4:5], v[0:1]
	v_pk_fma_f32 v[2:3], v[14:15], v[6:7], v[2:3]
	v_mul_f32_e32 v4, 0xbfb8aa3b, v0
	v_mul_f32_e32 v5, 0xbfb8aa3b, v1
	v_lshlrev_b32_e32 v20, 16, v56
	v_and_b32_e32 v21, 0xffff0000, v56
	v_mul_f32_e32 v6, 0xbfb8aa3b, v2
	v_mul_f32_e32 v7, 0xbfb8aa3b, v3
	v_exp_f32_e32 v4, v4
	v_exp_f32_e32 v5, v5
	v_pk_fma_f32 v[16:17], v[28:29], v[20:21], v[16:17]
	v_exp_f32_e32 v6, v6
	v_exp_f32_e32 v7, v7
	v_lshlrev_b32_e32 v22, 16, v57
	v_and_b32_e32 v23, 0xffff0000, v57
	v_mul_f32_e32 v20, 0xbfb8aa3b, v16
	v_mul_f32_e32 v21, 0xbfb8aa3b, v17
	v_pk_fma_f32 v[18:19], v[30:31], v[22:23], v[18:19]
	v_exp_f32_e32 v20, v20
	v_exp_f32_e32 v21, v21
	v_mul_f32_e32 v22, 0xbfb8aa3b, v18
	v_mul_f32_e32 v23, 0xbfb8aa3b, v19
	v_add_f32_e32 v4, 1.0, v4
	v_add_f32_e32 v5, 1.0, v5
	v_exp_f32_e32 v22, v22
	v_exp_f32_e32 v23, v23
	v_add_f32_e32 v6, 1.0, v6
	v_add_f32_e32 v7, 1.0, v7
	v_rcp_f32_e32 v4, v4
	v_rcp_f32_e32 v5, v5
	v_rcp_f32_e32 v6, v6
	v_rcp_f32_e32 v7, v7
	v_add_f32_e32 v20, 1.0, v20
	v_add_f32_e32 v21, 1.0, v21
	v_rcp_f32_e32 v20, v20
	v_rcp_f32_e32 v21, v21
	v_add_f32_e32 v22, 1.0, v22
	v_add_f32_e32 v23, 1.0, v23
	v_pk_mul_f32 v[0:1], v[0:1], v[4:5]
	v_rcp_f32_e32 v22, v22
	v_rcp_f32_e32 v23, v23
	v_pk_mul_f32 v[2:3], v[2:3], v[6:7]
	v_pk_mul_f32 v[4:5], v[0:1], v[0:1]
	v_pk_mul_f32 v[6:7], v[2:3], v[2:3]
	v_add_f32_e32 v4, v4, v5
	v_pk_mul_f32 v[16:17], v[16:17], v[20:21]
	v_add_f32_e32 v4, v6, v4
	v_pk_mul_f32 v[20:21], v[16:17], v[16:17]
	v_add_f32_e32 v4, v7, v4
	v_pk_mul_f32 v[18:19], v[18:19], v[22:23]
	v_add_f32_e32 v4, v20, v4
	v_pk_mul_f32 v[22:23], v[18:19], v[18:19]
	v_add_f32_e32 v4, v21, v4
	v_add_f32_e32 v4, v22, v4
	v_add_f32_e32 v4, v23, v4
	s_nop 1
	v_add_f32_dpp v4, v4, v4 row_ror:8 row_mask:0xf bank_mask:0xf
	s_nop 1
	v_add_f32_dpp v4, v4, v4 row_ror:4 row_mask:0xf bank_mask:0xf
	s_nop 1
	v_add_f32_dpp v4, v4, v4 row_ror:2 row_mask:0xf bank_mask:0xf
	s_nop 1
	v_add_f32_dpp v4, v4, v4 row_ror:1 row_mask:0xf bank_mask:0xf
	v_add_f32_e32 v4, 0x358637bd, v4
	v_cmp_gt_f32_e32 vcc, s66, v4
	v_mul_f32_e32 v5, 0x4b800000, v4
	s_nop 0
	v_cndmask_b32_e32 v4, v4, v5, vcc
	v_rsq_f32_e32 v4, v4
	s_nop 0
	v_mul_f32_e32 v5, 0x45800000, v4
	v_cndmask_b32_e32 v4, v4, v5, vcc
	v_cndmask_b32_e64 v4, v4, 1.0, s[4:5]
	v_pk_mul_f32 v[0:1], v[0:1], v[4:5] op_sel_hi:[1,0]
	v_pk_mul_f32 v[2:3], v[2:3], v[4:5] op_sel_hi:[1,0]
	v_cvt_pk_bf16_f32 v0, v0, v1
	v_cvt_pk_bf16_f32 v1, v2, v3
	v_pk_mul_f32 v[2:3], v[16:17], v[4:5] op_sel_hi:[1,0]
	v_pk_mul_f32 v[4:5], v[18:19], v[4:5] op_sel_hi:[1,0]
	v_cvt_pk_bf16_f32 v2, v2, v3
	v_cvt_pk_bf16_f32 v3, v4, v5
	ds_write_b128 v45, v[0:3] offset:8704
	s_cbranch_scc0 .LBB0_556
	s_ashr_i32 s11, s25, 6
	s_bfe_u32 s10, s11, 0x10001
	s_cmp_lt_i32 s11, 4
	s_cselect_b64 s[8:9], -1, 0
	s_cmp_gt_i32 s11, 3
	s_cselect_b64 s[6:7], -1, 0
	s_cmp_eq_u32 s10, 0
	s_cselect_b64 s[4:5], -1, 0
	s_bitcmp1_b32 s11, 0
	s_cselect_b64 s[12:13], -1, 0
	s_waitcnt lgkmcnt(0)
	s_barrier
	s_and_b64 s[4:5], s[12:13], s[4:5]
	s_and_b64 s[12:13], s[8:9], s[4:5]
	s_and_b64 vcc, exec, s[12:13]
	s_cbranch_vccnz .LBB0_626
	s_xor_b64 s[12:13], s[4:5], -1
	v_and_b32_e32 v17, 31, v64
	v_lshrrev_b32_e32 v16, 5, v36
	s_mov_b64 s[4:5], -1
	s_and_b64 vcc, exec, s[12:13]
	s_cbranch_vccz .LBB0_560
	s_and_b32 s11, s11, 1
	s_and_b64 s[4:5], s[8:9], exec
	s_mov_b32 s4, 0xca00
	s_cselect_b32 s4, 0x10e00, s4
	s_lshl_b32 s8, s10, 5
	v_or_b32_e32 v0, s8, v17
	s_add_i32 s4, s4, 0
	v_mul_u32_u24_e32 v0, 0x110, v0
	v_lshlrev_b32_e32 v4, 4, v16
	v_add3_u32 v26, s4, v0, v4
	ds_read_b128 v[0:3], v26
	v_lshl_or_b32 v46, s11, 5, v17
	v_mul_u32_u24_e32 v5, 0x110, v46
	s_add_i32 s4, 0, 0x10e00
	v_add3_u32 v27, s4, v5, v4
	ds_read_b128 v[4:7], v27
	s_waitcnt lgkmcnt(0)
	v_mfma_f32_32x32x16_bf16 v[0:15], v[0:3], v[4:7], 0
	ds_read_b128 v[18:21], v26 offset:32
	ds_read_b128 v[22:25], v27 offset:32
	s_mov_b64 s[4:5], 0
	s_waitcnt lgkmcnt(0)
	v_mfma_f32_32x32x16_bf16 v[0:15], v[18:21], v[22:25], v[0:15]
	ds_read_b128 v[18:21], v26 offset:64
	ds_read_b128 v[22:25], v27 offset:64
	s_waitcnt lgkmcnt(0)
	v_mfma_f32_32x32x16_bf16 v[0:15], v[18:21], v[22:25], v[0:15]
	ds_read_b128 v[18:21], v26 offset:96
	ds_read_b128 v[22:25], v27 offset:96
	s_waitcnt lgkmcnt(0)
	v_mfma_f32_32x32x16_bf16 v[0:15], v[18:21], v[22:25], v[0:15]
	ds_read_b128 v[18:21], v26 offset:128
	ds_read_b128 v[22:25], v27 offset:128
	s_waitcnt lgkmcnt(0)
	v_mfma_f32_32x32x16_bf16 v[0:15], v[18:21], v[22:25], v[0:15]
	ds_read_b128 v[18:21], v26 offset:160
	ds_read_b128 v[22:25], v27 offset:160
	s_waitcnt lgkmcnt(0)
	v_mfma_f32_32x32x16_bf16 v[0:15], v[18:21], v[22:25], v[0:15]
	ds_read_b128 v[18:21], v26 offset:192
	ds_read_b128 v[22:25], v27 offset:192
	s_waitcnt lgkmcnt(0)
	v_mfma_f32_32x32x16_bf16 v[0:15], v[18:21], v[22:25], v[0:15]
	ds_read_b128 v[18:21], v26 offset:224
	ds_read_b128 v[22:25], v27 offset:224
	s_waitcnt lgkmcnt(0)
	v_mfma_f32_32x32x16_bf16 v[0:15], v[18:21], v[22:25], v[0:15]
	v_mov_b32_e32 v18, s8

.LBB0_640:
	v_lshrrev_b32_e32 v20, 3, v44
	v_add_u32_e32 v20, v20, v45
	v_mul_lo_u32 v20, v20, 48
	v_sub_u32_e32 v44, v42, v20
	v_lshl_add_u64 v[20:21], s[28:29], 0, v[192:193]
	v_mov_b64_e32 v[22:23], s[20:21]
	v_mad_u64_u32 v[22:23], s[28:29], v20, s58, v[22:23]
	v_lshlrev_b32_e32 v20, 5, v44
	v_and_b32_e32 v20, 0xfffffe00, v20
	v_mad_i32_i24 v23, v21, s58, v23
	v_ashrrev_i32_e32 v21, 31, v20
	v_lshl_add_u64 v[20:21], v[20:21], 1, v[22:23]
	s_lshl_b32 s68, s37, 1
	v_lshlrev_b32_e32 v22, 4, v44
	v_lshl_add_u64 v[20:21], v[20:21], 0, s[68:69]
	v_and_b32_e32 v192, 0xf0, v22
	v_lshl_add_u64 v[20:21], v[20:21], 0, v[192:193]
	v_mov_b64_e32 v[20:21], v[226:227]
	v_mov_b64_e32 v[22:23], v[228:229]
	s_or_b64 exec, exec, s[18:19]
	s_and_saveexec_b64 s[18:19], vcc
	s_cbranch_execz .LBB0_547
.LBB0_641:
	v_mul_lo_u32 v44, v30, 48
	v_sub_u32_e32 v44, v64, v44
	v_mul_lo_u32 v30, v30, s59
	v_lshlrev_b32_e32 v44, 4, v44
	v_add_u32_e32 v30, 0, v30
	v_and_b32_e32 v45, 0xffffff00, v44
	v_and_b32_e32 v44, 0xf0, v44
	v_add3_u32 v30, v30, v45, v44
	ds_write_b128 v30, v[0:3]
	s_or_b64 exec, exec, s[18:19]
	s_and_saveexec_b64 s[18:19], s[4:5]
	s_cbranch_execz .LBB0_548
.LBB0_642:
	v_mul_lo_u32 v0, v32, 48
	v_sub_u32_e32 v0, v31, v0
	v_mul_lo_u32 v1, v32, s59
	v_lshlrev_b32_e32 v0, 4, v0
	v_add_u32_e32 v1, 0, v1
	v_and_b32_e32 v2, 0xffffff00, v0
	v_and_b32_e32 v0, 0xf0, v0
	v_add3_u32 v0, v1, v2, v0
	ds_write_b128 v0, v[8:11]
	s_or_b64 exec, exec, s[18:19]
	s_and_saveexec_b64 s[4:5], s[6:7]
	s_cbranch_execz .LBB0_549
.LBB0_643:
	v_mul_lo_u32 v0, v34, 48
	v_sub_u32_e32 v0, v33, v0
	v_mul_lo_u32 v1, v34, s59
	v_lshlrev_b32_e32 v0, 4, v0
	v_add_u32_e32 v1, 0, v1
	v_and_b32_e32 v2, 0xffffff00, v0
	v_and_b32_e32 v0, 0xf0, v0
	v_add3_u32 v0, v1, v2, v0
	ds_write_b128 v0, v[4:7]
	s_or_b64 exec, exec, s[4:5]
	s_and_saveexec_b64 s[4:5], s[8:9]
	s_cbranch_execz .LBB0_550
.LBB0_644:
	v_mul_lo_u32 v0, v37, 48
	v_sub_u32_e32 v0, v35, v0
	v_mul_lo_u32 v1, v37, s59
	v_lshlrev_b32_e32 v0, 4, v0
	v_add_u32_e32 v1, 0, v1
	v_and_b32_e32 v2, 0xffffff00, v0
	v_and_b32_e32 v0, 0xf0, v0
	v_add3_u32 v0, v1, v2, v0
	ds_write_b128 v0, v[16:19]
	s_or_b64 exec, exec, s[4:5]
	s_and_saveexec_b64 s[4:5], s[10:11]
	s_cbranch_execz .LBB0_551
.LBB0_645:
	v_mul_lo_u32 v0, v39, 48
	v_sub_u32_e32 v0, v38, v0
	v_mul_lo_u32 v1, v39, s59
	v_lshlrev_b32_e32 v0, 4, v0
	v_add_u32_e32 v1, 0, v1
	v_and_b32_e32 v2, 0xffffff00, v0
	v_and_b32_e32 v0, 0xf0, v0
	v_add3_u32 v0, v1, v2, v0
	ds_write_b128 v0, v[12:15]
	s_or_b64 exec, exec, s[4:5]
	s_and_saveexec_b64 s[4:5], s[12:13]
	s_cbranch_execz .LBB0_552
.LBB0_646:
	v_mul_lo_u32 v0, v41, 48
	v_sub_u32_e32 v0, v40, v0
	v_mul_lo_u32 v1, v41, s59
	v_lshlrev_b32_e32 v0, 4, v0
	v_add_u32_e32 v1, 0, v1
	v_and_b32_e32 v2, 0xffffff00, v0
	v_and_b32_e32 v0, 0xf0, v0
	v_add3_u32 v0, v1, v2, v0
	ds_write_b128 v0, v[24:27]
	s_or_b64 exec, exec, s[4:5]
	s_and_saveexec_b64 s[4:5], s[14:15]
	s_cbranch_execz .LBB0_553
.LBB0_647:
	v_mul_lo_u32 v0, v43, 48
	v_sub_u32_e32 v0, v42, v0
	v_mul_lo_u32 v1, v43, s59
	v_lshlrev_b32_e32 v0, 4, v0
	v_add_u32_e32 v1, 0, v1
	v_and_b32_e32 v2, 0xffffff00, v0
	v_and_b32_e32 v0, 0xf0, v0
	v_add3_u32 v0, v1, v2, v0
	ds_write_b128 v0, v[20:23]
	s_or_b64 exec, exec, s[4:5]
	s_and_b64 vcc, exec, s[26:27]
	s_cbranch_vccnz .LBB0_554
	s_branch .LBB0_555

.LBB0_709:
	s_lshr_b32 s24, s48, 3
	s_and_b32 s24, s24, 3
	s_lshl_b32 s56, s24, 5
	s_cmp_gt_i32 s55, 1
	v_lshl_add_u64 v[32:33], s[22:23], 0, v[192:193]
	s_cselect_b64 s[22:23], -1, 0
	s_cmp_gt_i32 s55, 55
	s_cselect_b32 s24, s54, 0
	s_add_i32 s24, s49, s24
	s_ashr_i32 s25, s24, 31
	s_cmp_gt_i32 s55, 47
	s_cselect_b32 s26, s54, 0
	s_add_i32 s26, s49, s26
	s_addk_i32 s26, 0x2000
	s_ashr_i32 s27, s26, 31
	s_cmp_gt_i32 s55, 39
	s_cselect_b32 s28, s54, 0
	s_add_i32 s28, s49, s28
	s_addk_i32 s28, 0x4000
	s_ashr_i32 s29, s28, 31
	s_cmp_gt_i32 s55, 31
	s_cselect_b32 s30, s54, 0
	s_add_i32 s30, s49, s30
	s_addk_i32 s30, 0x6000
	s_ashr_i32 s31, s30, 31
	s_cmp_gt_i32 s55, 23
	s_cselect_b32 s34, s54, 0
	s_add_i32 s34, s49, s34
	s_add_i32 s34, s34, 0x8000
	s_ashr_i32 s35, s34, 31
	s_cmp_gt_i32 s55, 15
	s_cselect_b32 s36, s54, 0
	s_add_i32 s36, s49, s36
	s_add_i32 s36, s36, 0xa000
	s_ashr_i32 s37, s36, 31
	s_cmp_gt_i32 s55, 7
	s_cselect_b32 s38, s54, 0
	s_add_i32 s38, s49, s38
	s_add_i32 s38, s38, 0xc000
	s_ashr_i32 s39, s38, 31
	s_cmp_gt_i32 s55, -1
	s_cselect_b32 s54, s54, 0
	s_ashr_i32 s91, s90, 31
	s_add_i32 s46, s47, s46
	v_and_b32_e32 v0, 15, v2
	s_add_i32 s86, s50, s54
	s_lshl_b32 s54, s55, 11
	s_lshl_b32 s57, s55, 4
	s_add_i32 s55, s46, 4
	s_lshl_b64 s[46:47], s[90:91], 24
	v_lshl_or_b32 v0, v0, 11, s46
	s_lshl_b32 s46, s48, 3
	v_lshrrev_b32_e32 v1, 1, v2
	s_and_b32 s46, s46, 0x300
	v_and_b32_e32 v1, 24, v1
	v_or3_b32 v0, v0, s46, v1
	s_add_i32 s46, s56, s57
	v_mov_b32_e32 v1, s47
	s_ashr_i32 s47, s46, 31
	s_ashr_i32 s87, s86, 31
	s_lshl_b64 s[46:47], s[46:47], 1
	s_add_u32 s46, s88, s46
	s_waitcnt vmcnt(0)
	s_addc_u32 s47, s89, s47
	v_mov_b32_e32 v20, v193
	v_mov_b32_e32 v21, v193
	v_mov_b32_e32 v22, v193
	v_mov_b32_e32 v23, v193
	v_lshlrev_b32_e32 v38, 5, v3
	v_lshl_add_u64 v[34:35], s[46:47], 0, v[0:1]
	v_mov_b64_e32 v[30:31], v[22:23]
	v_mov_b64_e32 v[26:27], v[22:23]
	v_mov_b64_e32 v[16:17], v[20:21]
	v_mov_b64_e32 v[12:13], v[20:21]
	v_mov_b64_e32 v[8:9], v[20:21]
	v_mov_b64_e32 v[4:5], v[20:21]
	v_mov_b64_e32 v[0:1], v[20:21]
	s_mov_b32 s51, 0
	s_add_i32 s56, 0, 0x20100
	s_mov_b64 s[88:89], 0
	v_mov_b64_e32 v[28:29], v[20:21]
	v_mov_b64_e32 v[24:25], v[20:21]
	v_mov_b64_e32 v[18:19], v[22:23]
	v_mov_b64_e32 v[14:15], v[22:23]
	v_mov_b64_e32 v[10:11], v[22:23]
	v_mov_b64_e32 v[6:7], v[22:23]
	v_mov_b64_e32 v[2:3], v[22:23]
	v_mov_b32_e32 v218, 0x1800
	v_mov_b32_e32 v219, 0
	s_add_i32 s61, s49, 0xfffff800
	v_mov_b32_e32 v220, s61
	v_mov_b32_e32 v221, 0
	s_lshl_b32 s68, s48, 9
	s_and_b32 s68, s68, 0x3000
	s_cmpk_gt_i32 s49, 0xfff
	s_cselect_b32 s68, s68, 0
	v_mov_b32_e32 v222, s68
	v_mov_b32_e32 v223, 0
	s_waitcnt vmcnt(0) lgkmcnt(0)
	s_barrier
	s_branch .LBB0_711

.LBB0_711:
	s_and_b32 s57, s51, 1
	s_cmp_eq_u32 s88, 0xfe0000
	s_cbranch_scc1 .Lscan_last
	s_and_b64 vcc, exec, s[22:23]
	s_cbranch_vccz .LBB0_721
	s_xor_b32 s60, s57, 1
	v_mad_i64_i32 v[36:37], s[46:47], s55, v245, v[32:33]
	s_mul_i32 s60, s60, 0xf000
	s_add_i32 s61, s60, s49
	s_addk_i32 s61, 0xf800
	v_lshl_add_u64 v[36:37], v[36:37], 0, v[220:221]
	s_mov_b32 m0, s61
	s_nop 0
	global_load_lds_dwordx4 v[36:37], off
	s_addk_i32 s61, 0x1800
	s_mov_b32 m0, s61
	v_lshl_add_u64 v[36:37], v[36:37], 0, v[218:219]
	global_load_lds_dwordx4 v[36:37], off
	s_addk_i32 s61, 0x1800
	s_mov_b32 m0, s61
	v_lshl_add_u64 v[36:37], v[36:37], 0, v[218:219]
	global_load_lds_dwordx4 v[36:37], off
	s_addk_i32 s61, 0x1800
	s_mov_b32 m0, s61
	v_lshl_add_u64 v[36:37], v[36:37], 0, v[218:219]
	global_load_lds_dwordx4 v[36:37], off
	s_addk_i32 s61, 0x1800
	s_mov_b32 m0, s61
	v_lshl_add_u64 v[36:37], v[36:37], 0, v[218:219]
	global_load_lds_dwordx4 v[36:37], off
	s_addk_i32 s61, 0x1800
	s_mov_b32 m0, s61
	v_lshl_add_u64 v[36:37], v[36:37], 0, v[218:219]
	global_load_lds_dwordx4 v[36:37], off
	s_addk_i32 s61, 0x1800
	s_mov_b32 m0, s61
	v_lshl_add_u64 v[36:37], v[36:37], 0, v[218:219]
	global_load_lds_dwordx4 v[36:37], off
	s_addk_i32 s61, 0x1800
	s_mov_b32 m0, s61
	v_lshl_add_u64 v[36:37], v[36:37], 0, v[218:219]
	global_load_lds_dwordx4 v[36:37], off
	s_addk_i32 s61, 0x1800
	s_mov_b32 m0, s61
	v_lshl_add_u64 v[36:37], v[36:37], 0, v[218:219]
	global_load_lds_dwordx4 v[36:37], off
	s_addk_i32 s61, 0x1800
	s_mov_b32 m0, s61
	v_lshl_add_u64 v[36:37], v[36:37], 0, v[218:219]
	v_lshl_add_u64 v[36:37], v[36:37], 0, v[222:223]
	global_load_lds_dwordx4 v[36:37], off
	s_waitcnt vmcnt(10)
	s_barrier
	s_waitcnt vmcnt(4)
	s_branch .LBB0_710
.Lscan_last:
	s_and_b64 vcc, exec, s[22:23]
	s_cbranch_vccz .LBB0_721
	s_waitcnt vmcnt(0)
	s_barrier
	s_branch .LBB0_710

.LBB0_723:
	s_andn2_b64 vcc, exec, s[46:47]
	s_cbranch_vccnz .LBB0_710
	s_mul_i32 s57, s57, 0xf000
	s_add_i32 s46, s57, 0
	v_mov_b32_e32 v36, s56
	v_add_u32_e32 v37, s46, v192
	ds_read_b32 v36, v36
	ds_read_b128 v[40:43], v37
	ds_read_b128 v[44:47], v37 offset:1024
	ds_read_b128 v[48:51], v37 offset:16384
	ds_read_b128 v[52:55], v37 offset:17408
	ds_read_b128 v[56:59], v37 offset:4096
	ds_read_b128 v[60:63], v37 offset:5120
	ds_read_b128 v[64:67], v37 offset:20480
	ds_read_b128 v[68:71], v37 offset:21504
	ds_read_b128 v[72:75], v37 offset:8192
	ds_read_b128 v[76:79], v37 offset:9216
	ds_read_b128 v[80:83], v37 offset:24576
	ds_read_b128 v[84:87], v37 offset:25600
	ds_read_b128 v[88:91], v37 offset:12288
	ds_read_b128 v[92:95], v37 offset:13312
	ds_read_b128 v[96:99], v37 offset:28672
	ds_read_b128 v[100:103], v37 offset:29696
	ds_read_b128 v[104:107], v37 offset:2048
	ds_read_b128 v[108:111], v37 offset:3072
	ds_read_b128 v[112:115], v37 offset:18432
	ds_read_b128 v[116:119], v37 offset:19456
	ds_read_b128 v[120:123], v37 offset:6144
	ds_read_b128 v[124:127], v37 offset:7168
	ds_read_b128 v[128:131], v37 offset:22528
	ds_read_b128 v[132:135], v37 offset:23552
	ds_read_b128 v[136:139], v37 offset:10240
	ds_read_b128 v[140:143], v37 offset:11264
	ds_read_b128 v[144:147], v37 offset:26624
	ds_read_b128 v[148:151], v37 offset:27648
	ds_read_b128 v[152:155], v37 offset:14336
	ds_read_b128 v[156:159], v37 offset:15360
	ds_read_b128 v[160:163], v37 offset:30720
	ds_read_b128 v[164:167], v37 offset:31744
	v_cvt_pk_bf16_f32 v168, v20, v21
	v_cvt_pk_bf16_f32 v169, v22, v23
	v_cvt_pk_bf16_f32 v170, v28, v29
	v_cvt_pk_bf16_f32 v171, v30, v31
	v_cvt_pk_bf16_f32 v172, v24, v25
	v_cvt_pk_bf16_f32 v173, v26, v27
	v_cvt_pk_bf16_f32 v174, v16, v17
	v_cvt_pk_bf16_f32 v175, v18, v19
	v_cvt_pk_bf16_f32 v176, v12, v13
	v_cvt_pk_bf16_f32 v177, v14, v15
	v_cvt_pk_bf16_f32 v178, v8, v9
	v_cvt_pk_bf16_f32 v179, v10, v11
	v_cvt_pk_bf16_f32 v180, v4, v5
	v_cvt_pk_bf16_f32 v181, v6, v7
	v_cvt_pk_bf16_f32 v182, v0, v1
	v_cvt_pk_bf16_f32 v183, v2, v3
	s_waitcnt lgkmcnt(0)
	v_mfma_f32_16x16x32_bf16 v[40:43], v[40:43], v[168:171], 0
	v_mfma_f32_16x16x32_bf16 v[56:59], v[56:59], v[168:171], 0
	v_mfma_f32_16x16x32_bf16 v[72:75], v[72:75], v[168:171], 0
	v_mfma_f32_16x16x32_bf16 v[88:91], v[88:91], v[168:171], 0
	v_mfma_f32_16x16x32_bf16 v[48:51], v[168:171], v[48:51], 0
	v_mfma_f32_16x16x32_bf16 v[64:67], v[168:171], v[64:67], 0
	v_mfma_f32_16x16x32_bf16 v[80:83], v[168:171], v[80:83], 0
	v_mfma_f32_16x16x32_bf16 v[96:99], v[168:171], v[96:99], 0
	v_mfma_f32_16x16x32_bf16 v[40:43], v[44:47], v[172:175], v[40:43]
	v_mfma_f32_16x16x32_bf16 v[44:47], v[60:63], v[172:175], v[56:59]
	v_mfma_f32_16x16x32_bf16 v[56:59], v[76:79], v[172:175], v[72:75]
	v_mfma_f32_16x16x32_bf16 v[60:63], v[92:95], v[172:175], v[88:91]
	v_mfma_f32_16x16x32_bf16 v[48:51], v[172:175], v[52:55], v[48:51]
	v_mfma_f32_16x16x32_bf16 v[52:55], v[172:175], v[68:71], v[64:67]
	v_mfma_f32_16x16x32_bf16 v[64:67], v[172:175], v[84:87], v[80:83]
	v_mfma_f32_16x16x32_bf16 v[68:71], v[172:175], v[100:103], v[96:99]
	s_barrier
	ds_read_b128 v[72:75], v37 offset:32768
	ds_read_b128 v[76:79], v37 offset:34816
	ds_read_b128 v[80:83], v37 offset:36864
	ds_read_b128 v[84:87], v37 offset:38912
	ds_read_b128 v[88:91], v37 offset:40960
	ds_read_b128 v[92:95], v37 offset:43008
	ds_read_b128 v[96:99], v37 offset:45056
	ds_read_b128 v[100:103], v37 offset:47104
	ds_read_b128 v[168:171], v37 offset:49152
	ds_read_b128 v[172:175], v37 offset:51200
	ds_read_b128 v[184:187], v37 offset:53248
	ds_read_b128 v[188:191], v37 offset:54272
	ds_read_b128 v[202:205], v37 offset:55296
	ds_read_b128 v[206:209], v37 offset:56320
	s_add_i32 s46, s46, s54
	v_add_u32_e32 v39, s46, v38
	ds_read_b128 v[210:213], v39 offset:57344
	ds_read_b128 v[214:217], v39 offset:57360
	v_mfma_f32_16x16x32_bf16 v[40:43], v[104:107], v[176:179], v[40:43]
	v_mfma_f32_16x16x32_bf16 v[44:47], v[120:123], v[176:179], v[44:47]
	v_mfma_f32_16x16x32_bf16 v[56:59], v[136:139], v[176:179], v[56:59]
	v_mfma_f32_16x16x32_bf16 v[60:63], v[152:155], v[176:179], v[60:63]
	v_mfma_f32_16x16x32_bf16 v[48:51], v[176:179], v[112:115], v[48:51]
	v_mfma_f32_16x16x32_bf16 v[52:55], v[176:179], v[128:131], v[52:55]
	v_mfma_f32_16x16x32_bf16 v[64:67], v[176:179], v[144:147], v[64:67]
	v_mfma_f32_16x16x32_bf16 v[68:71], v[176:179], v[160:163], v[68:71]
	v_mfma_f32_16x16x32_bf16 v[40:43], v[108:111], v[180:183], v[40:43]
	v_mfma_f32_16x16x32_bf16 v[44:47], v[124:127], v[180:183], v[44:47]
	v_mfma_f32_16x16x32_bf16 v[56:59], v[140:143], v[180:183], v[56:59]
	v_mfma_f32_16x16x32_bf16 v[60:63], v[156:159], v[180:183], v[60:63]
	v_mfma_f32_16x16x32_bf16 v[48:51], v[180:183], v[116:119], v[48:51]
	v_mfma_f32_16x16x32_bf16 v[52:55], v[180:183], v[132:135], v[52:55]
	v_mfma_f32_16x16x32_bf16 v[64:67], v[180:183], v[148:151], v[64:67]
	v_mfma_f32_16x16x32_bf16 v[68:71], v[180:183], v[164:167], v[68:71]
	ds_read_b128 v[104:107], v37 offset:33792
	ds_read_b128 v[108:111], v37 offset:35840
	ds_read_b128 v[112:115], v37 offset:37888
	ds_read_b128 v[116:119], v37 offset:39936
	ds_read_b128 v[120:123], v37 offset:41984
	ds_read_b128 v[124:127], v37 offset:44032
	ds_read_b128 v[128:131], v37 offset:46080
	ds_read_b128 v[132:135], v37 offset:48128
	s_waitcnt lgkmcnt(0)
	v_lshlrev_b32_e32 v37, 16, v210
	v_and_b32_e32 v39, 0xffff0000, v210
	v_lshlrev_b32_e32 v136, 16, v211
	v_and_b32_e32 v137, 0xffff0000, v211
	v_sub_f32_e32 v43, v137, v43
	v_sub_f32_e32 v42, v136, v42
	v_sub_f32_e32 v39, v39, v41
	v_sub_f32_e32 v37, v37, v40
	v_lshlrev_b32_e32 v40, 16, v212
	v_and_b32_e32 v41, 0xffff0000, v212
	v_lshlrev_b32_e32 v136, 16, v213
	v_and_b32_e32 v137, 0xffff0000, v213
	v_sub_f32_e32 v47, v137, v47
	v_sub_f32_e32 v46, v136, v46
	v_sub_f32_e32 v45, v41, v45
	v_sub_f32_e32 v44, v40, v44
	v_lshlrev_b32_e32 v40, 16, v214
	v_and_b32_e32 v41, 0xffff0000, v214
	v_lshlrev_b32_e32 v136, 16, v215
	v_and_b32_e32 v137, 0xffff0000, v215
	v_sub_f32_e32 v59, v137, v59
	v_sub_f32_e32 v58, v136, v58
	v_sub_f32_e32 v57, v41, v57
	v_sub_f32_e32 v56, v40, v56
	v_lshlrev_b32_e32 v40, 16, v216
	v_and_b32_e32 v41, 0xffff0000, v216
	v_lshlrev_b32_e32 v136, 16, v217
	v_and_b32_e32 v137, 0xffff0000, v217
	v_sub_f32_e32 v63, v137, v63
	v_sub_f32_e32 v62, v136, v62
	v_sub_f32_e32 v61, v41, v61
	v_sub_f32_e32 v60, v40, v60
	v_pk_mul_f32 v[22:23], v[22:23], v[36:37] op_sel_hi:[1,0]
	v_pk_mul_f32 v[20:21], v[20:21], v[36:37] op_sel_hi:[1,0]
	v_pk_mul_f32 v[30:31], v[30:31], v[36:37] op_sel_hi:[1,0]
	v_pk_mul_f32 v[28:29], v[28:29], v[36:37] op_sel_hi:[1,0]
	v_pk_mul_f32 v[26:27], v[26:27], v[36:37] op_sel_hi:[1,0]
	v_pk_mul_f32 v[24:25], v[24:25], v[36:37] op_sel_hi:[1,0]
	v_pk_mul_f32 v[18:19], v[18:19], v[36:37] op_sel_hi:[1,0]
	v_pk_mul_f32 v[16:17], v[16:17], v[36:37] op_sel_hi:[1,0]
	v_pk_mul_f32 v[14:15], v[14:15], v[36:37] op_sel_hi:[1,0]
	v_pk_mul_f32 v[12:13], v[12:13], v[36:37] op_sel_hi:[1,0]
	v_pk_mul_f32 v[10:11], v[10:11], v[36:37] op_sel_hi:[1,0]
	v_pk_mul_f32 v[8:9], v[8:9], v[36:37] op_sel_hi:[1,0]
	v_pk_mul_f32 v[6:7], v[6:7], v[36:37] op_sel_hi:[1,0]
	v_pk_mul_f32 v[4:5], v[4:5], v[36:37] op_sel_hi:[1,0]
	v_pk_mul_f32 v[2:3], v[2:3], v[36:37] op_sel_hi:[1,0]
	v_pk_mul_f32 v[0:1], v[0:1], v[36:37] op_sel_hi:[1,0]
	v_cvt_pk_bf16_f32 v40, v37, v39
	v_cvt_pk_bf16_f32 v41, v42, v43
	v_cvt_pk_bf16_f32 v42, v44, v45
	v_cvt_pk_bf16_f32 v43, v46, v47
	v_cvt_pk_bf16_f32 v44, v56, v57
	v_cvt_pk_bf16_f32 v45, v58, v59
	v_cvt_pk_bf16_f32 v46, v60, v61
	v_cvt_pk_bf16_f32 v47, v62, v63
	v_mfma_f32_16x16x32_bf16 v[20:23], v[72:75], v[40:43], v[20:23]
	v_mfma_f32_16x16x32_bf16 v[28:31], v[76:79], v[40:43], v[28:31]
	v_mfma_f32_16x16x32_bf16 v[24:27], v[80:83], v[40:43], v[24:27]
	v_mfma_f32_16x16x32_bf16 v[16:19], v[84:87], v[40:43], v[16:19]
	v_mfma_f32_16x16x32_bf16 v[12:15], v[88:91], v[40:43], v[12:15]
	v_mfma_f32_16x16x32_bf16 v[8:11], v[92:95], v[40:43], v[8:11]
	v_mfma_f32_16x16x32_bf16 v[4:7], v[96:99], v[40:43], v[4:7]
	v_mfma_f32_16x16x32_bf16 v[0:3], v[100:103], v[40:43], v[0:3]
	v_mfma_f32_16x16x32_bf16 v[48:51], v[40:43], v[168:171], v[48:51]
	v_mfma_f32_16x16x32_bf16 v[52:55], v[40:43], v[172:175], v[52:55]
	v_mfma_f32_16x16x32_bf16 v[56:59], v[40:43], v[184:187], v[64:67]
	v_mfma_f32_16x16x32_bf16 v[40:43], v[40:43], v[202:205], v[68:71]
	v_mfma_f32_16x16x32_bf16 v[20:23], v[104:107], v[44:47], v[20:23]
	v_mfma_f32_16x16x32_bf16 v[28:31], v[108:111], v[44:47], v[28:31]
	v_mfma_f32_16x16x32_bf16 v[24:27], v[112:115], v[44:47], v[24:27]
	v_mfma_f32_16x16x32_bf16 v[16:19], v[116:119], v[44:47], v[16:19]
	v_mfma_f32_16x16x32_bf16 v[12:15], v[120:123], v[44:47], v[12:15]
	v_mfma_f32_16x16x32_bf16 v[8:11], v[124:127], v[44:47], v[8:11]
	v_mfma_f32_16x16x32_bf16 v[4:7], v[128:131], v[44:47], v[4:7]
	v_mfma_f32_16x16x32_bf16 v[0:3], v[132:135], v[44:47], v[0:3]
	v_mfma_f32_16x16x32_bf16 v[56:59], v[44:47], v[188:191], v[56:59]
	v_mfma_f32_16x16x32_bf16 v[40:43], v[44:47], v[206:209], v[40:43]
	v_lshl_add_u64 v[36:37], v[34:35], 0, s[88:89]
	s_mov_b32 s46, 0xec00000
	v_add_co_u32_e32 v46, vcc, s46, v36
	v_cvt_pk_bf16_f32 v44, v48, v49
	v_cvt_pk_bf16_f32 v45, v50, v51
	v_addc_co_u32_e32 v47, vcc, 0, v37, vcc
	s_mov_b32 s46, 0xec08000
	global_store_dwordx2 v[46:47], v[44:45], off
	v_add_co_u32_e32 v46, vcc, s46, v36
	v_cvt_pk_bf16_f32 v44, v52, v53
	v_cvt_pk_bf16_f32 v45, v54, v55
	v_addc_co_u32_e32 v47, vcc, 0, v37, vcc
	s_mov_b32 s46, 0xec10000
	global_store_dwordx2 v[46:47], v[44:45], off
	v_add_co_u32_e32 v46, vcc, s46, v36
	v_cvt_pk_bf16_f32 v44, v56, v57
	s_nop 0
	v_addc_co_u32_e32 v47, vcc, 0, v37, vcc
	v_add_co_u32_e32 v36, vcc, 0xec18000, v36
	v_cvt_pk_bf16_f32 v45, v58, v59
	v_cvt_pk_bf16_f32 v40, v40, v41
	v_cvt_pk_bf16_f32 v41, v42, v43
	v_addc_co_u32_e32 v37, vcc, 0, v37, vcc
	global_store_dwordx2 v[46:47], v[44:45], off
	global_store_dwordx2 v[36:37], v[40:41], off
	s_waitcnt vmcnt(4) lgkmcnt(0)
	s_branch .LBB0_710
